# dense attention MFMA segments at priority 1 instead of 3
# baseline (speedup 1.0000x reference)
; __device__ __forceinline__ void qkt(f32x16& p0, f32x16& p1, const bf16_t* Ks, const bf16x8* qr, int r32, int hi) {
;   p0 = f32x16{}; p1 = f32x16{};
; #pragma unroll
;   for (int d0 = 0; d0 < 8; ++d0) { int cb = (d0 * 16 + hi * 8) * 2;
;     bf16x8 b0 = *reinterpret_cast<const bf16x8*>((const char*)Ks + KSWZ(r32, cb));
;     bf16x8 b1 = *reinterpret_cast<const bf16x8*>((const char*)Ks + KSWZ(32 + r32, cb));
;     p0 = __builtin_amdgcn_mfma_f32_32x32x16_bf16(b0, qr[d0], p0, 0, 0, 0);
;     p1 = __builtin_amdgcn_mfma_f32_32x32x16_bf16(b1, qr[d0], p1, 0, 0, 0); }
; }
.Lda_lead:
	s_setprio 1
	s_waitcnt vmcnt(4)
	ds_write_b128 v197, v[134:137] offset:32768
	ds_write_b128 v197, v[138:141] offset:40960
	ds_write_b128 v185, v[142:145] offset:32768
	ds_write_b128 v185, v[146:149] offset:40960
	s_waitcnt lgkmcnt(10)
	v_mfma_f32_32x32x16_bf16 v[80:95], v[150:153], v[130:133], 0
	v_mfma_f32_32x32x16_bf16 v[64:79], v[154:157], v[130:133], 0
	global_load_dwordx4 v[134:137], v184, s[16:17]
	global_load_dwordx4 v[138:141], v184, s[2:3]
	global_load_dwordx4 v[142:145], v184, s[14:15]
	global_load_dwordx4 v[146:149], v184, s[10:11]
	s_add_u32 s16, s16, 0x60000
	s_addc_u32 s17, s17, 0
	s_add_u32 s2, s2, 0x60000
	s_addc_u32 s3, s3, 0
	s_add_u32 s14, s14, 0x60000
	s_addc_u32 s15, s15, 0
	s_add_u32 s10, s10, 0x60000
	s_addc_u32 s11, s11, 0
	ds_read_b128 v[150:153], v208 offset:0
	ds_read_b128 v[154:157], v208 offset:8192
	s_waitcnt lgkmcnt(10)
	v_mfma_f32_32x32x16_bf16 v[80:95], v[158:161], v[126:129], v[80:95]
	v_mfma_f32_32x32x16_bf16 v[64:79], v[162:165], v[126:129], v[64:79]
	ds_read_b128 v[158:161], v209 offset:0
	ds_read_b128 v[162:165], v209 offset:8192
	s_waitcnt lgkmcnt(10)
	v_mfma_f32_32x32x16_bf16 v[80:95], v[228:231], v[122:125], v[80:95]
	v_mfma_f32_32x32x16_bf16 v[64:79], v[232:235], v[122:125], v[64:79]
	ds_read_b128 v[228:231], v210 offset:0
	ds_read_b128 v[232:235], v210 offset:8192
	s_waitcnt lgkmcnt(10)
	v_mfma_f32_32x32x16_bf16 v[80:95], v[236:239], v[118:121], v[80:95]
	v_mfma_f32_32x32x16_bf16 v[64:79], v[240:243], v[118:121], v[64:79]
	ds_read_b128 v[236:239], v211 offset:0
	ds_read_b128 v[240:243], v211 offset:8192
	s_waitcnt lgkmcnt(6)
	v_mfma_f32_32x32x16_bf16 v[80:95], v[150:153], v[114:117], v[80:95]
	v_mfma_f32_32x32x16_bf16 v[64:79], v[154:157], v[114:117], v[64:79]
	s_waitcnt lgkmcnt(4)
	v_mfma_f32_32x32x16_bf16 v[80:95], v[158:161], v[110:113], v[80:95]
	v_mfma_f32_32x32x16_bf16 v[64:79], v[162:165], v[110:113], v[64:79]
	s_waitcnt lgkmcnt(2)
	v_mfma_f32_32x32x16_bf16 v[80:95], v[228:231], v[106:109], v[80:95]
	v_mfma_f32_32x32x16_bf16 v[64:79], v[232:235], v[106:109], v[64:79]
	s_waitcnt lgkmcnt(0)
	v_mfma_f32_32x32x16_bf16 v[80:95], v[236:239], v[102:105], v[80:95]
	v_mfma_f32_32x32x16_bf16 v[64:79], v[240:243], v[102:105], v[64:79]
	s_nop 12
	s_setprio 0
	s_branch .Lda_y0
; #define SBAR() __builtin_amdgcn_sched_barrier(0)
; __device__ __forceinline__ void qkt(f32x16& p0, f32x16& p1, const bf16_t* Ks, const bf16x8* qr, int r32, int hi) {
;   p0 = f32x16{}; p1 = f32x16{};
; #pragma unroll
;   for (int d0 = 0; d0 < 8; ++d0) { int cb = (d0 * 16 + hi * 8) * 2;
;     bf16x8 b0 = *reinterpret_cast<const bf16x8*>((const char*)Ks + KSWZ(r32, cb));
;     bf16x8 b1 = *reinterpret_cast<const bf16x8*>((const char*)Ks + KSWZ(32 + r32, cb));
;     p0 = __builtin_amdgcn_mfma_f32_32x32x16_bf16(b0, qr[d0], p0, 0, 0, 0);
;     p1 = __builtin_amdgcn_mfma_f32_32x32x16_bf16(b1, qr[d0], p1, 0, 0, 0); }
; }
; __device__ __forceinline__ int v_st(int k, int c) { const int kk = (k & ~0xC) | ((k & 4) << 1) | ((k & 8) >> 1); return ((kk >> 3) * 4 + (c >> 5)) * 512 + ((kk & 7) * 32 + (c & 31)) * 2; }
; __device__ __forceinline__ int v_rd_base(int lane) { return ((lane & 3) << 3) | (((lane >> 2) & 3) << 6) | (((lane >> 4) & 1) << 5) | (((lane >> 5) & 1) << 8); }
; template <int OFF> __device__ __forceinline__ s16x4 tr_read(int vb) {
;   s16x4 r; asm volatile("ds_read_b64_tr_b16 %0, %1 offset:%2" : "=&v"(r) : "v"(vb), "i"(OFF) : "memory"); return r;
; }
; template <int D0> __device__ __forceinline__ void pv_one(f32x16& od, int vb, bf16x8 pa0, bf16x8 pa1, bf16x8 pa2, bf16x8 pa3) {
;   const s16x4 l0 = tr_read<v_rd_off(D0, 0, 0)>(vb), h0 = tr_read<v_rd_off(D0, 0, 1)>(vb), l1 = tr_read<v_rd_off(D0, 1, 0)>(vb), h1 = tr_read<v_rd_off(D0, 1, 1)>(vb);
;   const s16x4 l2 = tr_read<v_rd_off(D0, 2, 0)>(vb), h2 = tr_read<v_rd_off(D0, 2, 1)>(vb), l3 = tr_read<v_rd_off(D0, 3, 0)>(vb), h3 = tr_read<v_rd_off(D0, 3, 1)>(vb);
;   asm volatile("s_waitcnt lgkmcnt(0)" ::: "memory"); SBAR();
;     ...
;   od = __builtin_amdgcn_mfma_f32_32x32x16_bf16(pa0, PK(l0, h0), od, 0, 0, 0);
;   od = __builtin_amdgcn_mfma_f32_32x32x16_bf16(pa1, PK(l1, h1), od, 0, 0, 0);
;   od = __builtin_amdgcn_mfma_f32_32x32x16_bf16(pa2, PK(l2, h2), od, 0, 0, 0);
;   od = __builtin_amdgcn_mfma_f32_32x32x16_bf16(pa3, PK(l3, h3), od, 0, 0, 0);
;     ...
; }
; __device__ __forceinline__ void pv_d0(f32x16* o, int vb, bf16x8 pa0, bf16x8 pa1, bf16x8 pa2, bf16x8 pa3) {
;   pv_one<0>(o[0], vb, pa0, pa1, pa2, pa3); pv_one<1>(o[1], vb, pa0, pa1, pa2, pa3); pv_one<2>(o[2], vb, pa0, pa1, pa2, pa3); pv_one<3>(o[3], vb, pa0, pa1, pa2, pa3);
.Lda_loop:
	s_setprio 1
	s_waitcnt vmcnt(4)
	ds_write_b128 v197, v[134:137] offset:32768
	ds_write_b128 v197, v[138:141] offset:40960
	ds_write_b128 v185, v[142:145] offset:32768
	ds_write_b128 v185, v[146:149] offset:40960
	s_waitcnt lgkmcnt(10)
	v_mfma_f32_32x32x16_bf16 v[80:95], v[150:153], v[130:133], 0
	v_mfma_f32_32x32x16_bf16 v[64:79], v[154:157], v[130:133], 0
	global_load_dwordx4 v[134:137], v184, s[16:17]
	global_load_dwordx4 v[138:141], v184, s[2:3]
	global_load_dwordx4 v[142:145], v184, s[14:15]
	global_load_dwordx4 v[146:149], v184, s[10:11]
	s_add_u32 s16, s16, 0x60000
	s_addc_u32 s17, s17, 0
	s_add_u32 s2, s2, 0x60000
	s_addc_u32 s3, s3, 0
	s_add_u32 s14, s14, 0x60000
	s_addc_u32 s15, s15, 0
	s_add_u32 s10, s10, 0x60000
	s_addc_u32 s11, s11, 0
	ds_read_b128 v[150:153], v208 offset:0
	ds_read_b128 v[154:157], v208 offset:8192
	s_waitcnt lgkmcnt(10)
	v_mfma_f32_32x32x16_bf16 v[80:95], v[158:161], v[126:129], v[80:95]
	v_mfma_f32_32x32x16_bf16 v[64:79], v[162:165], v[126:129], v[64:79]
	ds_read_b128 v[158:161], v209 offset:0
	ds_read_b128 v[162:165], v209 offset:8192
	s_waitcnt lgkmcnt(10)
	v_mfma_f32_32x32x16_bf16 v[80:95], v[228:231], v[122:125], v[80:95]
	v_mfma_f32_32x32x16_bf16 v[64:79], v[232:235], v[122:125], v[64:79]
	ds_read_b128 v[228:231], v210 offset:0
	ds_read_b128 v[232:235], v210 offset:8192
	s_waitcnt lgkmcnt(10)
	v_mfma_f32_32x32x16_bf16 v[80:95], v[236:239], v[118:121], v[80:95]
	v_mfma_f32_32x32x16_bf16 v[64:79], v[240:243], v[118:121], v[64:79]
	ds_read_b128 v[236:239], v211 offset:0
	ds_read_b128 v[240:243], v211 offset:8192
	s_waitcnt lgkmcnt(6)
	v_mfma_f32_32x32x16_bf16 v[80:95], v[150:153], v[114:117], v[80:95]
	v_mfma_f32_32x32x16_bf16 v[64:79], v[154:157], v[114:117], v[64:79]
	ds_read_b64_tr_b16 v[150:151], v196 offset:49152
	ds_read_b64_tr_b16 v[152:153], v196 offset:51200
	ds_read_b64_tr_b16 v[154:155], v196 offset:53248
	ds_read_b64_tr_b16 v[156:157], v196 offset:55296
	s_waitcnt lgkmcnt(8)
	v_mfma_f32_32x32x16_bf16 v[80:95], v[158:161], v[110:113], v[80:95]
	v_mfma_f32_32x32x16_bf16 v[64:79], v[162:165], v[110:113], v[64:79]
	ds_read_b64_tr_b16 v[158:159], v196 offset:57344
	ds_read_b64_tr_b16 v[160:161], v196 offset:59392
	ds_read_b64_tr_b16 v[162:163], v196 offset:61440
	ds_read_b64_tr_b16 v[164:165], v196 offset:63488
	s_waitcnt lgkmcnt(10)
	v_mfma_f32_32x32x16_bf16 v[80:95], v[228:231], v[106:109], v[80:95]
	v_mfma_f32_32x32x16_bf16 v[64:79], v[232:235], v[106:109], v[64:79]
	ds_read_b64_tr_b16 v[228:229], v196 offset:49664
	ds_read_b64_tr_b16 v[230:231], v196 offset:51712
	ds_read_b64_tr_b16 v[232:233], v196 offset:53760
	ds_read_b64_tr_b16 v[234:235], v196 offset:55808
	s_waitcnt lgkmcnt(12)
	v_mfma_f32_32x32x16_bf16 v[80:95], v[236:239], v[102:105], v[80:95]
	v_mfma_f32_32x32x16_bf16 v[64:79], v[240:243], v[102:105], v[64:79]
	ds_read_b64_tr_b16 v[236:237], v196 offset:57856
	ds_read_b64_tr_b16 v[238:239], v196 offset:59904
	s_waitcnt lgkmcnt(12)
	v_mfma_f32_32x32x16_bf16 v[0:15], v[166:169], v[150:153], v[0:15]
	ds_read_b64_tr_b16 v[240:241], v196 offset:61952
	ds_read_b64_tr_b16 v[242:243], v196 offset:64000
	s_waitcnt lgkmcnt(12)
	v_mfma_f32_32x32x16_bf16 v[0:15], v[170:173], v[154:157], v[0:15]
	ds_read_b64_tr_b16 v[150:151], v196 offset:50176
	ds_read_b64_tr_b16 v[152:153], v196 offset:52224
	s_waitcnt lgkmcnt(12)
	v_mfma_f32_32x32x16_bf16 v[0:15], v[176:179], v[158:161], v[0:15]
	ds_read_b64_tr_b16 v[154:155], v196 offset:54272
	ds_read_b64_tr_b16 v[156:157], v196 offset:56320
	s_waitcnt lgkmcnt(12)
	v_mfma_f32_32x32x16_bf16 v[0:15], v[180:183], v[162:165], v[0:15]
	ds_read_b64_tr_b16 v[158:159], v196 offset:58368
	ds_read_b64_tr_b16 v[160:161], v196 offset:60416
	s_waitcnt lgkmcnt(12)
	v_mfma_f32_32x32x16_bf16 v[48:63], v[166:169], v[228:231], v[48:63]
	ds_read_b64_tr_b16 v[162:163], v196 offset:62464
	ds_read_b64_tr_b16 v[164:165], v196 offset:64512
	s_waitcnt lgkmcnt(12)
	v_mfma_f32_32x32x16_bf16 v[48:63], v[170:173], v[232:235], v[48:63]
	ds_read_b64_tr_b16 v[228:229], v196 offset:50688
	ds_read_b64_tr_b16 v[230:231], v196 offset:52736
	s_waitcnt lgkmcnt(12)
	v_mfma_f32_32x32x16_bf16 v[48:63], v[176:179], v[236:239], v[48:63]
	ds_read_b64_tr_b16 v[232:233], v196 offset:54784
	ds_read_b64_tr_b16 v[234:235], v196 offset:56832
	s_waitcnt lgkmcnt(12)
	v_mfma_f32_32x32x16_bf16 v[48:63], v[180:183], v[240:243], v[48:63]
	ds_read_b64_tr_b16 v[236:237], v196 offset:58880
	ds_read_b64_tr_b16 v[238:239], v196 offset:60928
	s_waitcnt lgkmcnt(12)
	v_mfma_f32_32x32x16_bf16 v[32:47], v[166:169], v[150:153], v[32:47]
	ds_read_b64_tr_b16 v[240:241], v196 offset:62976
	ds_read_b64_tr_b16 v[242:243], v196 offset:65024
	s_waitcnt lgkmcnt(12)
	v_mfma_f32_32x32x16_bf16 v[32:47], v[170:173], v[154:157], v[32:47]
	s_waitcnt lgkmcnt(10)
	v_mfma_f32_32x32x16_bf16 v[32:47], v[176:179], v[158:161], v[32:47]
	s_waitcnt lgkmcnt(8)
	v_mfma_f32_32x32x16_bf16 v[32:47], v[180:183], v[162:165], v[32:47]
	s_waitcnt lgkmcnt(6)
	v_mfma_f32_32x32x16_bf16 v[16:31], v[166:169], v[228:231], v[16:31]
	s_waitcnt lgkmcnt(4)
	v_mfma_f32_32x32x16_bf16 v[16:31], v[170:173], v[232:235], v[16:31]
	s_waitcnt lgkmcnt(2)
	v_mfma_f32_32x32x16_bf16 v[16:31], v[176:179], v[236:239], v[16:31]
	s_waitcnt lgkmcnt(0)
	v_mfma_f32_32x32x16_bf16 v[16:31], v[180:183], v[240:243], v[16:31]
	s_setprio 0

; #define SBAR() __builtin_amdgcn_sched_barrier(0)
; __device__ __forceinline__ void qkt(f32x16& p0, f32x16& p1, const bf16_t* Ks, const bf16x8* qr, int r32, int hi) {
;   p0 = f32x16{}; p1 = f32x16{};
; #pragma unroll
;   for (int d0 = 0; d0 < 8; ++d0) { int cb = (d0 * 16 + hi * 8) * 2;
;     bf16x8 b0 = *reinterpret_cast<const bf16x8*>((const char*)Ks + KSWZ(r32, cb));
;     bf16x8 b1 = *reinterpret_cast<const bf16x8*>((const char*)Ks + KSWZ(32 + r32, cb));
;     p0 = __builtin_amdgcn_mfma_f32_32x32x16_bf16(b0, qr[d0], p0, 0, 0, 0);
;     p1 = __builtin_amdgcn_mfma_f32_32x32x16_bf16(b1, qr[d0], p1, 0, 0, 0); }
; }
; __device__ __forceinline__ int v_st(int k, int c) { const int kk = (k & ~0xC) | ((k & 4) << 1) | ((k & 8) >> 1); return ((kk >> 3) * 4 + (c >> 5)) * 512 + ((kk & 7) * 32 + (c & 31)) * 2; }
; __device__ __forceinline__ int v_rd_base(int lane) { return ((lane & 3) << 3) | (((lane >> 2) & 3) << 6) | (((lane >> 4) & 1) << 5) | (((lane >> 5) & 1) << 8); }
; template <int OFF> __device__ __forceinline__ s16x4 tr_read(int vb) {
;   s16x4 r; asm volatile("ds_read_b64_tr_b16 %0, %1 offset:%2" : "=&v"(r) : "v"(vb), "i"(OFF) : "memory"); return r;
; }
; template <int D0> __device__ __forceinline__ void pv_one(f32x16& od, int vb, bf16x8 pa0, bf16x8 pa1, bf16x8 pa2, bf16x8 pa3) {
;   const s16x4 l0 = tr_read<v_rd_off(D0, 0, 0)>(vb), h0 = tr_read<v_rd_off(D0, 0, 1)>(vb), l1 = tr_read<v_rd_off(D0, 1, 0)>(vb), h1 = tr_read<v_rd_off(D0, 1, 1)>(vb);
;   const s16x4 l2 = tr_read<v_rd_off(D0, 2, 0)>(vb), h2 = tr_read<v_rd_off(D0, 2, 1)>(vb), l3 = tr_read<v_rd_off(D0, 3, 0)>(vb), h3 = tr_read<v_rd_off(D0, 3, 1)>(vb);
;   asm volatile("s_waitcnt lgkmcnt(0)" ::: "memory"); SBAR();
;     ...
;   od = __builtin_amdgcn_mfma_f32_32x32x16_bf16(pa0, PK(l0, h0), od, 0, 0, 0);
;   od = __builtin_amdgcn_mfma_f32_32x32x16_bf16(pa1, PK(l1, h1), od, 0, 0, 0);
;   od = __builtin_amdgcn_mfma_f32_32x32x16_bf16(pa2, PK(l2, h2), od, 0, 0, 0);
;   od = __builtin_amdgcn_mfma_f32_32x32x16_bf16(pa3, PK(l3, h3), od, 0, 0, 0);
;     ...
; }
; __device__ __forceinline__ void pv_d0(f32x16* o, int vb, bf16x8 pa0, bf16x8 pa1, bf16x8 pa2, bf16x8 pa3) {
;   pv_one<0>(o[0], vb, pa0, pa1, pa2, pa3); pv_one<1>(o[1], vb, pa0, pa1, pa2, pa3); pv_one<2>(o[2], vb, pa0, pa1, pa2, pa3); pv_one<3>(o[3], vb, pa0, pa1, pa2, pa3);
.Lda_skipk_0:
	s_barrier
	s_setprio 1
	s_waitcnt vmcnt(4)
	ds_write_b128 v197, v[186:189] offset:49152
	ds_write_b128 v197, v[220:223] offset:57344
	ds_write_b128 v185, v[246:249] offset:49152
	ds_write_b128 v185, v[200:203] offset:57344
	s_waitcnt lgkmcnt(10)
	v_mfma_f32_32x32x16_bf16 v[80:95], v[150:153], v[130:133], 0
	v_mfma_f32_32x32x16_bf16 v[64:79], v[154:157], v[130:133], 0
	global_load_dwordx4 v[186:189], v184, s[16:17]
	global_load_dwordx4 v[220:223], v184, s[2:3]
	global_load_dwordx4 v[246:249], v184, s[14:15]
	global_load_dwordx4 v[200:203], v184, s[10:11]
	s_add_u32 s16, s16, 0x60000
	s_addc_u32 s17, s17, 0
	s_add_u32 s2, s2, 0x60000
	s_addc_u32 s3, s3, 0
	s_add_u32 s14, s14, 0x60000
	s_addc_u32 s15, s15, 0
	s_add_u32 s10, s10, 0x60000
	s_addc_u32 s11, s11, 0
	ds_read_b128 v[150:153], v208 offset:16384
	ds_read_b128 v[154:157], v208 offset:24576
	s_waitcnt lgkmcnt(10)
	v_mfma_f32_32x32x16_bf16 v[80:95], v[158:161], v[126:129], v[80:95]
	v_mfma_f32_32x32x16_bf16 v[64:79], v[162:165], v[126:129], v[64:79]
	ds_read_b128 v[158:161], v209 offset:16384
	ds_read_b128 v[162:165], v209 offset:24576
	s_waitcnt lgkmcnt(10)
	v_mfma_f32_32x32x16_bf16 v[80:95], v[228:231], v[122:125], v[80:95]
	v_mfma_f32_32x32x16_bf16 v[64:79], v[232:235], v[122:125], v[64:79]
	ds_read_b128 v[228:231], v210 offset:16384
	ds_read_b128 v[232:235], v210 offset:24576
	s_waitcnt lgkmcnt(10)
	v_mfma_f32_32x32x16_bf16 v[80:95], v[236:239], v[118:121], v[80:95]
	v_mfma_f32_32x32x16_bf16 v[64:79], v[240:243], v[118:121], v[64:79]
	ds_read_b128 v[236:239], v211 offset:16384
	ds_read_b128 v[240:243], v211 offset:24576
	s_waitcnt lgkmcnt(6)
	v_mfma_f32_32x32x16_bf16 v[80:95], v[150:153], v[114:117], v[80:95]
	v_mfma_f32_32x32x16_bf16 v[64:79], v[154:157], v[114:117], v[64:79]
	ds_read_b64_tr_b16 v[150:151], v196 offset:0
	ds_read_b64_tr_b16 v[152:153], v196 offset:2048
	ds_read_b64_tr_b16 v[154:155], v196 offset:4096
	ds_read_b64_tr_b16 v[156:157], v196 offset:6144
	s_waitcnt lgkmcnt(8)
	v_mfma_f32_32x32x16_bf16 v[80:95], v[158:161], v[110:113], v[80:95]
	v_mfma_f32_32x32x16_bf16 v[64:79], v[162:165], v[110:113], v[64:79]
	ds_read_b64_tr_b16 v[158:159], v196 offset:8192
	ds_read_b64_tr_b16 v[160:161], v196 offset:10240
	ds_read_b64_tr_b16 v[162:163], v196 offset:12288
	ds_read_b64_tr_b16 v[164:165], v196 offset:14336
	s_waitcnt lgkmcnt(10)
	v_mfma_f32_32x32x16_bf16 v[80:95], v[228:231], v[106:109], v[80:95]
	v_mfma_f32_32x32x16_bf16 v[64:79], v[232:235], v[106:109], v[64:79]
	ds_read_b64_tr_b16 v[228:229], v196 offset:512
	ds_read_b64_tr_b16 v[230:231], v196 offset:2560
	ds_read_b64_tr_b16 v[232:233], v196 offset:4608
	ds_read_b64_tr_b16 v[234:235], v196 offset:6656
	s_waitcnt lgkmcnt(12)
	v_mfma_f32_32x32x16_bf16 v[80:95], v[236:239], v[102:105], v[80:95]
	v_mfma_f32_32x32x16_bf16 v[64:79], v[240:243], v[102:105], v[64:79]
	ds_read_b64_tr_b16 v[236:237], v196 offset:8704
	ds_read_b64_tr_b16 v[238:239], v196 offset:10752
	s_waitcnt lgkmcnt(12)
	v_mfma_f32_32x32x16_bf16 v[0:15], v[166:169], v[150:153], v[0:15]
	ds_read_b64_tr_b16 v[240:241], v196 offset:12800
	ds_read_b64_tr_b16 v[242:243], v196 offset:14848
	s_waitcnt lgkmcnt(12)
	v_mfma_f32_32x32x16_bf16 v[0:15], v[170:173], v[154:157], v[0:15]
	ds_read_b64_tr_b16 v[150:151], v196 offset:1024
	ds_read_b64_tr_b16 v[152:153], v196 offset:3072
	s_waitcnt lgkmcnt(12)
	v_mfma_f32_32x32x16_bf16 v[0:15], v[176:179], v[158:161], v[0:15]
	ds_read_b64_tr_b16 v[154:155], v196 offset:5120
	ds_read_b64_tr_b16 v[156:157], v196 offset:7168
	s_waitcnt lgkmcnt(12)
	v_mfma_f32_32x32x16_bf16 v[0:15], v[180:183], v[162:165], v[0:15]
	ds_read_b64_tr_b16 v[158:159], v196 offset:9216
	ds_read_b64_tr_b16 v[160:161], v196 offset:11264
	s_waitcnt lgkmcnt(12)
	v_mfma_f32_32x32x16_bf16 v[48:63], v[166:169], v[228:231], v[48:63]
	ds_read_b64_tr_b16 v[162:163], v196 offset:13312
	ds_read_b64_tr_b16 v[164:165], v196 offset:15360
	s_waitcnt lgkmcnt(12)
	v_mfma_f32_32x32x16_bf16 v[48:63], v[170:173], v[232:235], v[48:63]
	ds_read_b64_tr_b16 v[228:229], v196 offset:1536
	ds_read_b64_tr_b16 v[230:231], v196 offset:3584
	s_waitcnt lgkmcnt(12)
	v_mfma_f32_32x32x16_bf16 v[48:63], v[176:179], v[236:239], v[48:63]
	ds_read_b64_tr_b16 v[232:233], v196 offset:5632
	ds_read_b64_tr_b16 v[234:235], v196 offset:7680
	s_waitcnt lgkmcnt(12)
	v_mfma_f32_32x32x16_bf16 v[48:63], v[180:183], v[240:243], v[48:63]
	ds_read_b64_tr_b16 v[236:237], v196 offset:9728
	ds_read_b64_tr_b16 v[238:239], v196 offset:11776
	s_waitcnt lgkmcnt(12)
	v_mfma_f32_32x32x16_bf16 v[32:47], v[166:169], v[150:153], v[32:47]
	ds_read_b64_tr_b16 v[240:241], v196 offset:13824
	ds_read_b64_tr_b16 v[242:243], v196 offset:15872
	s_waitcnt lgkmcnt(12)
	v_mfma_f32_32x32x16_bf16 v[32:47], v[170:173], v[154:157], v[32:47]
	s_waitcnt lgkmcnt(10)
	v_mfma_f32_32x32x16_bf16 v[32:47], v[176:179], v[158:161], v[32:47]
	s_waitcnt lgkmcnt(8)
	v_mfma_f32_32x32x16_bf16 v[32:47], v[180:183], v[162:165], v[32:47]
	s_waitcnt lgkmcnt(6)
	v_mfma_f32_32x32x16_bf16 v[16:31], v[166:169], v[228:231], v[16:31]
	s_waitcnt lgkmcnt(4)
	v_mfma_f32_32x32x16_bf16 v[16:31], v[170:173], v[232:235], v[16:31]
	s_waitcnt lgkmcnt(2)
	v_mfma_f32_32x32x16_bf16 v[16:31], v[176:179], v[236:239], v[16:31]
	s_waitcnt lgkmcnt(0)
	v_mfma_f32_32x32x16_bf16 v[16:31], v[180:183], v[240:243], v[16:31]
	s_setprio 0
	s_barrier
; __device__ __forceinline__ void partialSM(f32x16& p0, f32x16& p1, float& m_reg, float& mn, float& alpha) {
;   constexpr float C = SCALE * 1.4426950408889634f;
;   float pmax = p0[0];
; #pragma unroll
;   for (int r = 1; r < 16; ++r) pmax = fmaxf(pmax, p0[r]);
; #pragma unroll
;   for (int r = 0; r < 16; ++r) pmax = fmaxf(pmax, p1[r]);
;   { auto rr = __builtin_amdgcn_permlane32_swap(__float_as_uint(pmax), __float_as_uint(pmax), false, false);
;     pmax = fmaxf(__uint_as_float(rr[0]), __uint_as_float(rr[1])); }
;   if (__builtin_expect(__all(pmax - m_reg <= THR / SCALE), 1)) { mn = m_reg; alpha = 1.f; }
;   else { mn = fmaxf(m_reg, pmax); alpha = __builtin_amdgcn_exp2f((m_reg - mn) * C); m_reg = mn; }
	v_max3_f32 v190, v80, v81, v82
	v_max3_f32 v191, v64, v65, v66
	v_max3_f32 v190, v190, v83, v84
	v_max3_f32 v191, v191, v67, v68
	v_max3_f32 v190, v190, v85, v86
	v_max3_f32 v191, v191, v69, v70
	v_max3_f32 v190, v190, v87, v88
	v_max3_f32 v191, v191, v71, v72
	v_max3_f32 v190, v190, v89, v90
	v_max3_f32 v191, v191, v73, v74
	v_max3_f32 v190, v190, v91, v92
	v_max3_f32 v191, v191, v75, v76
	v_max3_f32 v190, v190, v93, v94
	v_max3_f32 v191, v191, v77, v78
	v_max3_f32 v190, v190, v95, v79
	v_max_f32_e32 v190, v190, v191
	v_mov_b32_e32 v191, v190
	s_nop 1
	v_permlane32_swap_b32_e32 v190, v191
	s_nop 0
	v_max_f32_e32 v212, v190, v191
	v_sub_f32_e32 v190, v212, v174
	v_cmp_ge_f32_e32 vcc, s86, v190
	s_nop 3
	s_cmp_eq_u64 vcc, exec
	s_cbranch_scc1 .Lda_common_1
	v_max_f32_e32 v191, v174, v212
	v_sub_f32_e32 v215, v174, v191
	v_mul_f32_e32 v215, s92, v215
	v_exp_f32_e32 v213, v215
	v_mov_b32_e32 v174, v191
	v_mul_f32_e32 v214, 0xbe0293ee, v174
	v_mul_f32_e32 v175, v175, v213
	s_and_saveexec_b64 s[12:13], s[40:41]
	ds_write_b32 v199, v213 offset:128
	s_or_b64 exec, exec, s[12:13]
	s_waitcnt lgkmcnt(0)
	v_add_u32_e32 v215, v99, v96
	ds_read_b128 v[228:231], v215 offset:128
	ds_read_b128 v[232:235], v215 offset:160
	ds_read_b128 v[236:239], v215 offset:192
	ds_read_b128 v[240:243], v215 offset:224
	s_waitcnt lgkmcnt(0)
	v_pk_mul_f32 v[0:1], v[0:1], v[228:229]
	v_pk_mul_f32 v[2:3], v[2:3], v[230:231]
	v_pk_mul_f32 v[4:5], v[4:5], v[232:233]
	v_pk_mul_f32 v[6:7], v[6:7], v[234:235]
	v_pk_mul_f32 v[8:9], v[8:9], v[236:237]
	v_pk_mul_f32 v[10:11], v[10:11], v[238:239]
	v_pk_mul_f32 v[12:13], v[12:13], v[240:241]
	v_pk_mul_f32 v[14:15], v[14:15], v[242:243]
	v_pk_mul_f32 v[48:49], v[48:49], v[228:229]
	v_pk_mul_f32 v[50:51], v[50:51], v[230:231]
	v_pk_mul_f32 v[52:53], v[52:53], v[232:233]
	v_pk_mul_f32 v[54:55], v[54:55], v[234:235]
	v_pk_mul_f32 v[56:57], v[56:57], v[236:237]
	v_pk_mul_f32 v[58:59], v[58:59], v[238:239]
	v_pk_mul_f32 v[60:61], v[60:61], v[240:241]
	v_pk_mul_f32 v[62:63], v[62:63], v[242:243]
	v_pk_mul_f32 v[32:33], v[32:33], v[228:229]
	v_pk_mul_f32 v[34:35], v[34:35], v[230:231]
	v_pk_mul_f32 v[36:37], v[36:37], v[232:233]
	v_pk_mul_f32 v[38:39], v[38:39], v[234:235]
	v_pk_mul_f32 v[40:41], v[40:41], v[236:237]
	v_pk_mul_f32 v[42:43], v[42:43], v[238:239]
	v_pk_mul_f32 v[44:45], v[44:45], v[240:241]
	v_pk_mul_f32 v[46:47], v[46:47], v[242:243]
	v_pk_mul_f32 v[16:17], v[16:17], v[228:229]
	v_pk_mul_f32 v[18:19], v[18:19], v[230:231]
	v_pk_mul_f32 v[20:21], v[20:21], v[232:233]
	v_pk_mul_f32 v[22:23], v[22:23], v[234:235]
	v_pk_mul_f32 v[24:25], v[24:25], v[236:237]
	v_pk_mul_f32 v[26:27], v[26:27], v[238:239]
	v_pk_mul_f32 v[28:29], v[28:29], v[240:241]
	v_pk_mul_f32 v[30:31], v[30:31], v[242:243]

; #define SBAR() __builtin_amdgcn_sched_barrier(0)
; __device__ __forceinline__ void qkt(f32x16& p0, f32x16& p1, const bf16_t* Ks, const bf16x8* qr, int r32, int hi) {
;   p0 = f32x16{}; p1 = f32x16{};
; #pragma unroll
;   for (int d0 = 0; d0 < 8; ++d0) { int cb = (d0 * 16 + hi * 8) * 2;
;     bf16x8 b0 = *reinterpret_cast<const bf16x8*>((const char*)Ks + KSWZ(r32, cb));
;     bf16x8 b1 = *reinterpret_cast<const bf16x8*>((const char*)Ks + KSWZ(32 + r32, cb));
;     p0 = __builtin_amdgcn_mfma_f32_32x32x16_bf16(b0, qr[d0], p0, 0, 0, 0);
;     p1 = __builtin_amdgcn_mfma_f32_32x32x16_bf16(b1, qr[d0], p1, 0, 0, 0); }
; }
; __device__ __forceinline__ int v_st(int k, int c) { const int kk = (k & ~0xC) | ((k & 4) << 1) | ((k & 8) >> 1); return ((kk >> 3) * 4 + (c >> 5)) * 512 + ((kk & 7) * 32 + (c & 31)) * 2; }
; __device__ __forceinline__ int v_rd_base(int lane) { return ((lane & 3) << 3) | (((lane >> 2) & 3) << 6) | (((lane >> 4) & 1) << 5) | (((lane >> 5) & 1) << 8); }
; template <int OFF> __device__ __forceinline__ s16x4 tr_read(int vb) {
;   s16x4 r; asm volatile("ds_read_b64_tr_b16 %0, %1 offset:%2" : "=&v"(r) : "v"(vb), "i"(OFF) : "memory"); return r;
; }
; template <int D0> __device__ __forceinline__ void pv_one(f32x16& od, int vb, bf16x8 pa0, bf16x8 pa1, bf16x8 pa2, bf16x8 pa3) {
;   const s16x4 l0 = tr_read<v_rd_off(D0, 0, 0)>(vb), h0 = tr_read<v_rd_off(D0, 0, 1)>(vb), l1 = tr_read<v_rd_off(D0, 1, 0)>(vb), h1 = tr_read<v_rd_off(D0, 1, 1)>(vb);
;   const s16x4 l2 = tr_read<v_rd_off(D0, 2, 0)>(vb), h2 = tr_read<v_rd_off(D0, 2, 1)>(vb), l3 = tr_read<v_rd_off(D0, 3, 0)>(vb), h3 = tr_read<v_rd_off(D0, 3, 1)>(vb);
;   asm volatile("s_waitcnt lgkmcnt(0)" ::: "memory"); SBAR();
;     ...
;   od = __builtin_amdgcn_mfma_f32_32x32x16_bf16(pa0, PK(l0, h0), od, 0, 0, 0);
;   od = __builtin_amdgcn_mfma_f32_32x32x16_bf16(pa1, PK(l1, h1), od, 0, 0, 0);
;   od = __builtin_amdgcn_mfma_f32_32x32x16_bf16(pa2, PK(l2, h2), od, 0, 0, 0);
;   od = __builtin_amdgcn_mfma_f32_32x32x16_bf16(pa3, PK(l3, h3), od, 0, 0, 0);
;     ...
; }
; __device__ __forceinline__ void pv_d0(f32x16* o, int vb, bf16x8 pa0, bf16x8 pa1, bf16x8 pa2, bf16x8 pa3) {
;   pv_one<0>(o[0], vb, pa0, pa1, pa2, pa3); pv_one<1>(o[1], vb, pa0, pa1, pa2, pa3); pv_one<2>(o[2], vb, pa0, pa1, pa2, pa3); pv_one<3>(o[3], vb, pa0, pa1, pa2, pa3);
.Lda_skipk_1:
	s_barrier
	s_setprio 1
	s_waitcnt vmcnt(4)
	ds_write_b128 v197, v[134:137] offset:0
	ds_write_b128 v197, v[138:141] offset:8192
	ds_write_b128 v185, v[142:145] offset:0
	ds_write_b128 v185, v[146:149] offset:8192
	s_waitcnt lgkmcnt(10)
	v_mfma_f32_32x32x16_bf16 v[80:95], v[150:153], v[130:133], 0
	v_mfma_f32_32x32x16_bf16 v[64:79], v[154:157], v[130:133], 0
	global_load_dwordx4 v[134:137], v184, s[16:17]
	global_load_dwordx4 v[138:141], v184, s[2:3]
	global_load_dwordx4 v[142:145], v184, s[14:15]
	global_load_dwordx4 v[146:149], v184, s[10:11]
	s_add_u32 s16, s16, 0x60000
	s_addc_u32 s17, s17, 0
	s_add_u32 s2, s2, 0x60000
	s_addc_u32 s3, s3, 0
	s_add_u32 s14, s14, 0x60000
	s_addc_u32 s15, s15, 0
	s_add_u32 s10, s10, 0x60000
	s_addc_u32 s11, s11, 0
	ds_read_b128 v[150:153], v208 offset:32768
	ds_read_b128 v[154:157], v208 offset:40960
	s_waitcnt lgkmcnt(10)
	v_mfma_f32_32x32x16_bf16 v[80:95], v[158:161], v[126:129], v[80:95]
	v_mfma_f32_32x32x16_bf16 v[64:79], v[162:165], v[126:129], v[64:79]
	ds_read_b128 v[158:161], v209 offset:32768
	ds_read_b128 v[162:165], v209 offset:40960
	s_waitcnt lgkmcnt(10)
	v_mfma_f32_32x32x16_bf16 v[80:95], v[228:231], v[122:125], v[80:95]
	v_mfma_f32_32x32x16_bf16 v[64:79], v[232:235], v[122:125], v[64:79]
	ds_read_b128 v[228:231], v210 offset:32768
	ds_read_b128 v[232:235], v210 offset:40960
	s_waitcnt lgkmcnt(10)
	v_mfma_f32_32x32x16_bf16 v[80:95], v[236:239], v[118:121], v[80:95]
	v_mfma_f32_32x32x16_bf16 v[64:79], v[240:243], v[118:121], v[64:79]
	ds_read_b128 v[236:239], v211 offset:32768
	ds_read_b128 v[240:243], v211 offset:40960
	s_waitcnt lgkmcnt(6)
	v_mfma_f32_32x32x16_bf16 v[80:95], v[150:153], v[114:117], v[80:95]
	v_mfma_f32_32x32x16_bf16 v[64:79], v[154:157], v[114:117], v[64:79]
	ds_read_b64_tr_b16 v[150:151], v196 offset:16384
	ds_read_b64_tr_b16 v[152:153], v196 offset:18432
	ds_read_b64_tr_b16 v[154:155], v196 offset:20480
	ds_read_b64_tr_b16 v[156:157], v196 offset:22528
	s_waitcnt lgkmcnt(8)
	v_mfma_f32_32x32x16_bf16 v[80:95], v[158:161], v[110:113], v[80:95]
	v_mfma_f32_32x32x16_bf16 v[64:79], v[162:165], v[110:113], v[64:79]
	ds_read_b64_tr_b16 v[158:159], v196 offset:24576
	ds_read_b64_tr_b16 v[160:161], v196 offset:26624
	ds_read_b64_tr_b16 v[162:163], v196 offset:28672
	ds_read_b64_tr_b16 v[164:165], v196 offset:30720
	s_waitcnt lgkmcnt(10)
	v_mfma_f32_32x32x16_bf16 v[80:95], v[228:231], v[106:109], v[80:95]
	v_mfma_f32_32x32x16_bf16 v[64:79], v[232:235], v[106:109], v[64:79]
	ds_read_b64_tr_b16 v[228:229], v196 offset:16896
	ds_read_b64_tr_b16 v[230:231], v196 offset:18944
	ds_read_b64_tr_b16 v[232:233], v196 offset:20992
	ds_read_b64_tr_b16 v[234:235], v196 offset:23040
	s_waitcnt lgkmcnt(12)
	v_mfma_f32_32x32x16_bf16 v[80:95], v[236:239], v[102:105], v[80:95]
	v_mfma_f32_32x32x16_bf16 v[64:79], v[240:243], v[102:105], v[64:79]
	ds_read_b64_tr_b16 v[236:237], v196 offset:25088
	ds_read_b64_tr_b16 v[238:239], v196 offset:27136
	s_waitcnt lgkmcnt(12)
	v_mfma_f32_32x32x16_bf16 v[0:15], v[166:169], v[150:153], v[0:15]
	ds_read_b64_tr_b16 v[240:241], v196 offset:29184
	ds_read_b64_tr_b16 v[242:243], v196 offset:31232
	s_waitcnt lgkmcnt(12)
	v_mfma_f32_32x32x16_bf16 v[0:15], v[170:173], v[154:157], v[0:15]
	ds_read_b64_tr_b16 v[150:151], v196 offset:17408
	ds_read_b64_tr_b16 v[152:153], v196 offset:19456
	s_waitcnt lgkmcnt(12)
	v_mfma_f32_32x32x16_bf16 v[0:15], v[176:179], v[158:161], v[0:15]
	ds_read_b64_tr_b16 v[154:155], v196 offset:21504
	ds_read_b64_tr_b16 v[156:157], v196 offset:23552
	s_waitcnt lgkmcnt(12)
	v_mfma_f32_32x32x16_bf16 v[0:15], v[180:183], v[162:165], v[0:15]
	ds_read_b64_tr_b16 v[158:159], v196 offset:25600
	ds_read_b64_tr_b16 v[160:161], v196 offset:27648
	s_waitcnt lgkmcnt(12)
	v_mfma_f32_32x32x16_bf16 v[48:63], v[166:169], v[228:231], v[48:63]
	ds_read_b64_tr_b16 v[162:163], v196 offset:29696
	ds_read_b64_tr_b16 v[164:165], v196 offset:31744
	s_waitcnt lgkmcnt(12)
	v_mfma_f32_32x32x16_bf16 v[48:63], v[170:173], v[232:235], v[48:63]
	ds_read_b64_tr_b16 v[228:229], v196 offset:17920
	ds_read_b64_tr_b16 v[230:231], v196 offset:19968
	s_waitcnt lgkmcnt(12)
	v_mfma_f32_32x32x16_bf16 v[48:63], v[176:179], v[236:239], v[48:63]
	ds_read_b64_tr_b16 v[232:233], v196 offset:22016
	ds_read_b64_tr_b16 v[234:235], v196 offset:24064
	s_waitcnt lgkmcnt(12)
	v_mfma_f32_32x32x16_bf16 v[48:63], v[180:183], v[240:243], v[48:63]
	ds_read_b64_tr_b16 v[236:237], v196 offset:26112
	ds_read_b64_tr_b16 v[238:239], v196 offset:28160
	s_waitcnt lgkmcnt(12)
	v_mfma_f32_32x32x16_bf16 v[32:47], v[166:169], v[150:153], v[32:47]
	ds_read_b64_tr_b16 v[240:241], v196 offset:30208
	ds_read_b64_tr_b16 v[242:243], v196 offset:32256
	s_waitcnt lgkmcnt(12)
	v_mfma_f32_32x32x16_bf16 v[32:47], v[170:173], v[154:157], v[32:47]
	s_waitcnt lgkmcnt(10)
	v_mfma_f32_32x32x16_bf16 v[32:47], v[176:179], v[158:161], v[32:47]
	s_waitcnt lgkmcnt(8)
	v_mfma_f32_32x32x16_bf16 v[32:47], v[180:183], v[162:165], v[32:47]
	s_waitcnt lgkmcnt(6)
	v_mfma_f32_32x32x16_bf16 v[16:31], v[166:169], v[228:231], v[16:31]
	s_waitcnt lgkmcnt(4)
	v_mfma_f32_32x32x16_bf16 v[16:31], v[170:173], v[232:235], v[16:31]
	s_waitcnt lgkmcnt(2)
	v_mfma_f32_32x32x16_bf16 v[16:31], v[176:179], v[236:239], v[16:31]
	s_waitcnt lgkmcnt(0)
	v_mfma_f32_32x32x16_bf16 v[16:31], v[180:183], v[240:243], v[16:31]
	s_setprio 0
	s_barrier
; __device__ __forceinline__ void partialSM(f32x16& p0, f32x16& p1, float& m_reg, float& mn, float& alpha) {
;   constexpr float C = SCALE * 1.4426950408889634f;
;   float pmax = p0[0];
; #pragma unroll
;   for (int r = 1; r < 16; ++r) pmax = fmaxf(pmax, p0[r]);
; #pragma unroll
;   for (int r = 0; r < 16; ++r) pmax = fmaxf(pmax, p1[r]);
;   { auto rr = __builtin_amdgcn_permlane32_swap(__float_as_uint(pmax), __float_as_uint(pmax), false, false);
;     pmax = fmaxf(__uint_as_float(rr[0]), __uint_as_float(rr[1])); }
;   if (__builtin_expect(__all(pmax - m_reg <= THR / SCALE), 1)) { mn = m_reg; alpha = 1.f; }
;   else { mn = fmaxf(m_reg, pmax); alpha = __builtin_amdgcn_exp2f((m_reg - mn) * C); m_reg = mn; }
	v_max3_f32 v190, v80, v81, v82
	v_max3_f32 v191, v64, v65, v66
	v_max3_f32 v190, v190, v83, v84
	v_max3_f32 v191, v191, v67, v68
	v_max3_f32 v190, v190, v85, v86
	v_max3_f32 v191, v191, v69, v70
	v_max3_f32 v190, v190, v87, v88
	v_max3_f32 v191, v191, v71, v72
	v_max3_f32 v190, v190, v89, v90
	v_max3_f32 v191, v191, v73, v74
	v_max3_f32 v190, v190, v91, v92
	v_max3_f32 v191, v191, v75, v76
	v_max3_f32 v190, v190, v93, v94
	v_max3_f32 v191, v191, v77, v78
	v_max3_f32 v190, v190, v95, v79
	v_max_f32_e32 v190, v190, v191
	v_mov_b32_e32 v191, v190
	s_nop 1
	v_permlane32_swap_b32_e32 v190, v191
	s_nop 0
	v_max_f32_e32 v212, v190, v191
	v_sub_f32_e32 v190, v212, v174
	v_cmp_ge_f32_e32 vcc, s86, v190
	s_nop 3
	s_cmp_eq_u64 vcc, exec
	s_cbranch_scc1 .Lda_common_2
	v_max_f32_e32 v191, v174, v212
	v_sub_f32_e32 v215, v174, v191
	v_mul_f32_e32 v215, s92, v215
	v_exp_f32_e32 v213, v215
	v_mov_b32_e32 v174, v191
	v_mul_f32_e32 v214, 0xbe0293ee, v174
	v_mul_f32_e32 v175, v175, v213
	s_and_saveexec_b64 s[12:13], s[40:41]
	ds_write_b32 v199, v213 offset:128
	s_or_b64 exec, exec, s[12:13]
	s_waitcnt lgkmcnt(0)
	v_add_u32_e32 v215, v99, v96
	ds_read_b128 v[228:231], v215 offset:128
	ds_read_b128 v[232:235], v215 offset:160
	ds_read_b128 v[236:239], v215 offset:192
	ds_read_b128 v[240:243], v215 offset:224
	s_waitcnt lgkmcnt(0)
	v_pk_mul_f32 v[0:1], v[0:1], v[228:229]
	v_pk_mul_f32 v[2:3], v[2:3], v[230:231]
	v_pk_mul_f32 v[4:5], v[4:5], v[232:233]
	v_pk_mul_f32 v[6:7], v[6:7], v[234:235]
	v_pk_mul_f32 v[8:9], v[8:9], v[236:237]
	v_pk_mul_f32 v[10:11], v[10:11], v[238:239]
	v_pk_mul_f32 v[12:13], v[12:13], v[240:241]
	v_pk_mul_f32 v[14:15], v[14:15], v[242:243]
	v_pk_mul_f32 v[48:49], v[48:49], v[228:229]
	v_pk_mul_f32 v[50:51], v[50:51], v[230:231]
	v_pk_mul_f32 v[52:53], v[52:53], v[232:233]
	v_pk_mul_f32 v[54:55], v[54:55], v[234:235]
	v_pk_mul_f32 v[56:57], v[56:57], v[236:237]
	v_pk_mul_f32 v[58:59], v[58:59], v[238:239]
	v_pk_mul_f32 v[60:61], v[60:61], v[240:241]
	v_pk_mul_f32 v[62:63], v[62:63], v[242:243]
	v_pk_mul_f32 v[32:33], v[32:33], v[228:229]
	v_pk_mul_f32 v[34:35], v[34:35], v[230:231]
	v_pk_mul_f32 v[36:37], v[36:37], v[232:233]
	v_pk_mul_f32 v[38:39], v[38:39], v[234:235]
	v_pk_mul_f32 v[40:41], v[40:41], v[236:237]
	v_pk_mul_f32 v[42:43], v[42:43], v[238:239]
	v_pk_mul_f32 v[44:45], v[44:45], v[240:241]
	v_pk_mul_f32 v[46:47], v[46:47], v[242:243]
	v_pk_mul_f32 v[16:17], v[16:17], v[228:229]
	v_pk_mul_f32 v[18:19], v[18:19], v[230:231]
	v_pk_mul_f32 v[20:21], v[20:21], v[232:233]
	v_pk_mul_f32 v[22:23], v[22:23], v[234:235]
	v_pk_mul_f32 v[24:25], v[24:25], v[236:237]
	v_pk_mul_f32 v[26:27], v[26:27], v[238:239]
	v_pk_mul_f32 v[28:29], v[28:29], v[240:241]
	v_pk_mul_f32 v[30:31], v[30:31], v[242:243]

; #define SBAR() __builtin_amdgcn_sched_barrier(0)
; __device__ __forceinline__ void qkt(f32x16& p0, f32x16& p1, const bf16_t* Ks, const bf16x8* qr, int r32, int hi) {
;   p0 = f32x16{}; p1 = f32x16{};
; #pragma unroll
;   for (int d0 = 0; d0 < 8; ++d0) { int cb = (d0 * 16 + hi * 8) * 2;
;     bf16x8 b0 = *reinterpret_cast<const bf16x8*>((const char*)Ks + KSWZ(r32, cb));
;     bf16x8 b1 = *reinterpret_cast<const bf16x8*>((const char*)Ks + KSWZ(32 + r32, cb));
;     p0 = __builtin_amdgcn_mfma_f32_32x32x16_bf16(b0, qr[d0], p0, 0, 0, 0);
;     p1 = __builtin_amdgcn_mfma_f32_32x32x16_bf16(b1, qr[d0], p1, 0, 0, 0); }
; }
; __device__ __forceinline__ int v_st(int k, int c) { const int kk = (k & ~0xC) | ((k & 4) << 1) | ((k & 8) >> 1); return ((kk >> 3) * 4 + (c >> 5)) * 512 + ((kk & 7) * 32 + (c & 31)) * 2; }
; __device__ __forceinline__ int v_rd_base(int lane) { return ((lane & 3) << 3) | (((lane >> 2) & 3) << 6) | (((lane >> 4) & 1) << 5) | (((lane >> 5) & 1) << 8); }
; template <int OFF> __device__ __forceinline__ s16x4 tr_read(int vb) {
;   s16x4 r; asm volatile("ds_read_b64_tr_b16 %0, %1 offset:%2" : "=&v"(r) : "v"(vb), "i"(OFF) : "memory"); return r;
; }
; template <int D0> __device__ __forceinline__ void pv_one(f32x16& od, int vb, bf16x8 pa0, bf16x8 pa1, bf16x8 pa2, bf16x8 pa3) {
;   const s16x4 l0 = tr_read<v_rd_off(D0, 0, 0)>(vb), h0 = tr_read<v_rd_off(D0, 0, 1)>(vb), l1 = tr_read<v_rd_off(D0, 1, 0)>(vb), h1 = tr_read<v_rd_off(D0, 1, 1)>(vb);
;   const s16x4 l2 = tr_read<v_rd_off(D0, 2, 0)>(vb), h2 = tr_read<v_rd_off(D0, 2, 1)>(vb), l3 = tr_read<v_rd_off(D0, 3, 0)>(vb), h3 = tr_read<v_rd_off(D0, 3, 1)>(vb);
;   asm volatile("s_waitcnt lgkmcnt(0)" ::: "memory"); SBAR();
;     ...
;   od = __builtin_amdgcn_mfma_f32_32x32x16_bf16(pa0, PK(l0, h0), od, 0, 0, 0);
;   od = __builtin_amdgcn_mfma_f32_32x32x16_bf16(pa1, PK(l1, h1), od, 0, 0, 0);
;   od = __builtin_amdgcn_mfma_f32_32x32x16_bf16(pa2, PK(l2, h2), od, 0, 0, 0);
;   od = __builtin_amdgcn_mfma_f32_32x32x16_bf16(pa3, PK(l3, h3), od, 0, 0, 0);
;     ...
; }
; __device__ __forceinline__ void pv_d0(f32x16* o, int vb, bf16x8 pa0, bf16x8 pa1, bf16x8 pa2, bf16x8 pa3) {
;   pv_one<0>(o[0], vb, pa0, pa1, pa2, pa3); pv_one<1>(o[1], vb, pa0, pa1, pa2, pa3); pv_one<2>(o[2], vb, pa0, pa1, pa2, pa3); pv_one<3>(o[3], vb, pa0, pa1, pa2, pa3);
.Lda_skipk_2:
	s_barrier
	s_setprio 1
	s_waitcnt vmcnt(4)
	ds_write_b128 v197, v[186:189] offset:16384
	ds_write_b128 v197, v[220:223] offset:24576
	ds_write_b128 v185, v[246:249] offset:16384
	ds_write_b128 v185, v[200:203] offset:24576
	s_waitcnt lgkmcnt(10)
	v_mfma_f32_32x32x16_bf16 v[80:95], v[150:153], v[130:133], 0
	v_mfma_f32_32x32x16_bf16 v[64:79], v[154:157], v[130:133], 0
	global_load_dwordx4 v[186:189], v184, s[16:17]
	global_load_dwordx4 v[220:223], v184, s[2:3]
	global_load_dwordx4 v[246:249], v184, s[14:15]
	global_load_dwordx4 v[200:203], v184, s[10:11]
	s_add_u32 s16, s16, 0x60000
	s_addc_u32 s17, s17, 0
	s_add_u32 s2, s2, 0x60000
	s_addc_u32 s3, s3, 0
	s_add_u32 s14, s14, 0x60000
	s_addc_u32 s15, s15, 0
	s_add_u32 s10, s10, 0x60000
	s_addc_u32 s11, s11, 0
	ds_read_b128 v[150:153], v208 offset:49152
	ds_read_b128 v[154:157], v208 offset:57344
	s_waitcnt lgkmcnt(10)
	v_mfma_f32_32x32x16_bf16 v[80:95], v[158:161], v[126:129], v[80:95]
	v_mfma_f32_32x32x16_bf16 v[64:79], v[162:165], v[126:129], v[64:79]
	ds_read_b128 v[158:161], v209 offset:49152
	ds_read_b128 v[162:165], v209 offset:57344
	s_waitcnt lgkmcnt(10)
	v_mfma_f32_32x32x16_bf16 v[80:95], v[228:231], v[122:125], v[80:95]
	v_mfma_f32_32x32x16_bf16 v[64:79], v[232:235], v[122:125], v[64:79]
	ds_read_b128 v[228:231], v210 offset:49152
	ds_read_b128 v[232:235], v210 offset:57344
	s_waitcnt lgkmcnt(10)
	v_mfma_f32_32x32x16_bf16 v[80:95], v[236:239], v[118:121], v[80:95]
	v_mfma_f32_32x32x16_bf16 v[64:79], v[240:243], v[118:121], v[64:79]
	ds_read_b128 v[236:239], v211 offset:49152
	ds_read_b128 v[240:243], v211 offset:57344
	s_waitcnt lgkmcnt(6)
	v_mfma_f32_32x32x16_bf16 v[80:95], v[150:153], v[114:117], v[80:95]
	v_mfma_f32_32x32x16_bf16 v[64:79], v[154:157], v[114:117], v[64:79]
	ds_read_b64_tr_b16 v[150:151], v196 offset:32768
	ds_read_b64_tr_b16 v[152:153], v196 offset:34816
	ds_read_b64_tr_b16 v[154:155], v196 offset:36864
	ds_read_b64_tr_b16 v[156:157], v196 offset:38912
	s_waitcnt lgkmcnt(8)
	v_mfma_f32_32x32x16_bf16 v[80:95], v[158:161], v[110:113], v[80:95]
	v_mfma_f32_32x32x16_bf16 v[64:79], v[162:165], v[110:113], v[64:79]
	ds_read_b64_tr_b16 v[158:159], v196 offset:40960
	ds_read_b64_tr_b16 v[160:161], v196 offset:43008
	ds_read_b64_tr_b16 v[162:163], v196 offset:45056
	ds_read_b64_tr_b16 v[164:165], v196 offset:47104
	s_waitcnt lgkmcnt(10)
	v_mfma_f32_32x32x16_bf16 v[80:95], v[228:231], v[106:109], v[80:95]
	v_mfma_f32_32x32x16_bf16 v[64:79], v[232:235], v[106:109], v[64:79]
	ds_read_b64_tr_b16 v[228:229], v196 offset:33280
	ds_read_b64_tr_b16 v[230:231], v196 offset:35328
	ds_read_b64_tr_b16 v[232:233], v196 offset:37376
	ds_read_b64_tr_b16 v[234:235], v196 offset:39424
	s_waitcnt lgkmcnt(12)
	v_mfma_f32_32x32x16_bf16 v[80:95], v[236:239], v[102:105], v[80:95]
	v_mfma_f32_32x32x16_bf16 v[64:79], v[240:243], v[102:105], v[64:79]
	ds_read_b64_tr_b16 v[236:237], v196 offset:41472
	ds_read_b64_tr_b16 v[238:239], v196 offset:43520
	s_waitcnt lgkmcnt(12)
	v_mfma_f32_32x32x16_bf16 v[0:15], v[166:169], v[150:153], v[0:15]
	ds_read_b64_tr_b16 v[240:241], v196 offset:45568
	ds_read_b64_tr_b16 v[242:243], v196 offset:47616
	s_waitcnt lgkmcnt(12)
	v_mfma_f32_32x32x16_bf16 v[0:15], v[170:173], v[154:157], v[0:15]
	ds_read_b64_tr_b16 v[150:151], v196 offset:33792
	ds_read_b64_tr_b16 v[152:153], v196 offset:35840
	s_waitcnt lgkmcnt(12)
	v_mfma_f32_32x32x16_bf16 v[0:15], v[176:179], v[158:161], v[0:15]
	ds_read_b64_tr_b16 v[154:155], v196 offset:37888
	ds_read_b64_tr_b16 v[156:157], v196 offset:39936
	s_waitcnt lgkmcnt(12)
	v_mfma_f32_32x32x16_bf16 v[0:15], v[180:183], v[162:165], v[0:15]
	ds_read_b64_tr_b16 v[158:159], v196 offset:41984
	ds_read_b64_tr_b16 v[160:161], v196 offset:44032
	s_waitcnt lgkmcnt(12)
	v_mfma_f32_32x32x16_bf16 v[48:63], v[166:169], v[228:231], v[48:63]
	ds_read_b64_tr_b16 v[162:163], v196 offset:46080
	ds_read_b64_tr_b16 v[164:165], v196 offset:48128
	s_waitcnt lgkmcnt(12)
	v_mfma_f32_32x32x16_bf16 v[48:63], v[170:173], v[232:235], v[48:63]
	ds_read_b64_tr_b16 v[228:229], v196 offset:34304
	ds_read_b64_tr_b16 v[230:231], v196 offset:36352
	s_waitcnt lgkmcnt(12)
	v_mfma_f32_32x32x16_bf16 v[48:63], v[176:179], v[236:239], v[48:63]
	ds_read_b64_tr_b16 v[232:233], v196 offset:38400
	ds_read_b64_tr_b16 v[234:235], v196 offset:40448
	s_waitcnt lgkmcnt(12)
	v_mfma_f32_32x32x16_bf16 v[48:63], v[180:183], v[240:243], v[48:63]
	ds_read_b64_tr_b16 v[236:237], v196 offset:42496
	ds_read_b64_tr_b16 v[238:239], v196 offset:44544
	s_waitcnt lgkmcnt(12)
	v_mfma_f32_32x32x16_bf16 v[32:47], v[166:169], v[150:153], v[32:47]
	ds_read_b64_tr_b16 v[240:241], v196 offset:46592
	ds_read_b64_tr_b16 v[242:243], v196 offset:48640
	s_waitcnt lgkmcnt(12)
	v_mfma_f32_32x32x16_bf16 v[32:47], v[170:173], v[154:157], v[32:47]
	s_waitcnt lgkmcnt(10)
	v_mfma_f32_32x32x16_bf16 v[32:47], v[176:179], v[158:161], v[32:47]
	s_waitcnt lgkmcnt(8)
	v_mfma_f32_32x32x16_bf16 v[32:47], v[180:183], v[162:165], v[32:47]
	s_waitcnt lgkmcnt(6)
	v_mfma_f32_32x32x16_bf16 v[16:31], v[166:169], v[228:231], v[16:31]
	s_waitcnt lgkmcnt(4)
	v_mfma_f32_32x32x16_bf16 v[16:31], v[170:173], v[232:235], v[16:31]
	s_waitcnt lgkmcnt(2)
	v_mfma_f32_32x32x16_bf16 v[16:31], v[176:179], v[236:239], v[16:31]
	s_waitcnt lgkmcnt(0)
	v_mfma_f32_32x32x16_bf16 v[16:31], v[180:183], v[240:243], v[16:31]
	s_setprio 0
	s_barrier
; __device__ __forceinline__ void partialSM(f32x16& p0, f32x16& p1, float& m_reg, float& mn, float& alpha) {
;   constexpr float C = SCALE * 1.4426950408889634f;
;   float pmax = p0[0];
; #pragma unroll
;   for (int r = 1; r < 16; ++r) pmax = fmaxf(pmax, p0[r]);
; #pragma unroll
;   for (int r = 0; r < 16; ++r) pmax = fmaxf(pmax, p1[r]);
;   { auto rr = __builtin_amdgcn_permlane32_swap(__float_as_uint(pmax), __float_as_uint(pmax), false, false);
;     pmax = fmaxf(__uint_as_float(rr[0]), __uint_as_float(rr[1])); }
;   if (__builtin_expect(__all(pmax - m_reg <= THR / SCALE), 1)) { mn = m_reg; alpha = 1.f; }
;   else { mn = fmaxf(m_reg, pmax); alpha = __builtin_amdgcn_exp2f((m_reg - mn) * C); m_reg = mn; }
	v_max3_f32 v190, v80, v81, v82
	v_max3_f32 v191, v64, v65, v66
	v_max3_f32 v190, v190, v83, v84
	v_max3_f32 v191, v191, v67, v68
	v_max3_f32 v190, v190, v85, v86
	v_max3_f32 v191, v191, v69, v70
	v_max3_f32 v190, v190, v87, v88
	v_max3_f32 v191, v191, v71, v72
	v_max3_f32 v190, v190, v89, v90
	v_max3_f32 v191, v191, v73, v74
	v_max3_f32 v190, v190, v91, v92
	v_max3_f32 v191, v191, v75, v76
	v_max3_f32 v190, v190, v93, v94
	v_max3_f32 v191, v191, v77, v78
	v_max3_f32 v190, v190, v95, v79
	v_max_f32_e32 v190, v190, v191
	v_mov_b32_e32 v191, v190
	s_nop 1
	v_permlane32_swap_b32_e32 v190, v191
	s_nop 0
	v_max_f32_e32 v212, v190, v191
	v_sub_f32_e32 v190, v212, v174
	v_cmp_ge_f32_e32 vcc, s86, v190
	s_nop 3
	s_cmp_eq_u64 vcc, exec
	s_cbranch_scc1 .Lda_common_3
	v_max_f32_e32 v191, v174, v212
	v_sub_f32_e32 v215, v174, v191
	v_mul_f32_e32 v215, s92, v215
	v_exp_f32_e32 v213, v215
	v_mov_b32_e32 v174, v191
	v_mul_f32_e32 v214, 0xbe0293ee, v174
	v_mul_f32_e32 v175, v175, v213
	s_and_saveexec_b64 s[12:13], s[40:41]
	ds_write_b32 v199, v213 offset:128
	s_or_b64 exec, exec, s[12:13]
	s_waitcnt lgkmcnt(0)
	v_add_u32_e32 v215, v99, v96
	ds_read_b128 v[228:231], v215 offset:128
	ds_read_b128 v[232:235], v215 offset:160
	ds_read_b128 v[236:239], v215 offset:192
	ds_read_b128 v[240:243], v215 offset:224
	s_waitcnt lgkmcnt(0)
	v_pk_mul_f32 v[0:1], v[0:1], v[228:229]
	v_pk_mul_f32 v[2:3], v[2:3], v[230:231]
	v_pk_mul_f32 v[4:5], v[4:5], v[232:233]
	v_pk_mul_f32 v[6:7], v[6:7], v[234:235]
	v_pk_mul_f32 v[8:9], v[8:9], v[236:237]
	v_pk_mul_f32 v[10:11], v[10:11], v[238:239]
	v_pk_mul_f32 v[12:13], v[12:13], v[240:241]
	v_pk_mul_f32 v[14:15], v[14:15], v[242:243]
	v_pk_mul_f32 v[48:49], v[48:49], v[228:229]
	v_pk_mul_f32 v[50:51], v[50:51], v[230:231]
	v_pk_mul_f32 v[52:53], v[52:53], v[232:233]
	v_pk_mul_f32 v[54:55], v[54:55], v[234:235]
	v_pk_mul_f32 v[56:57], v[56:57], v[236:237]
	v_pk_mul_f32 v[58:59], v[58:59], v[238:239]
	v_pk_mul_f32 v[60:61], v[60:61], v[240:241]
	v_pk_mul_f32 v[62:63], v[62:63], v[242:243]
	v_pk_mul_f32 v[32:33], v[32:33], v[228:229]
	v_pk_mul_f32 v[34:35], v[34:35], v[230:231]
	v_pk_mul_f32 v[36:37], v[36:37], v[232:233]
	v_pk_mul_f32 v[38:39], v[38:39], v[234:235]
	v_pk_mul_f32 v[40:41], v[40:41], v[236:237]
	v_pk_mul_f32 v[42:43], v[42:43], v[238:239]
	v_pk_mul_f32 v[44:45], v[44:45], v[240:241]
	v_pk_mul_f32 v[46:47], v[46:47], v[242:243]
	v_pk_mul_f32 v[16:17], v[16:17], v[228:229]
	v_pk_mul_f32 v[18:19], v[18:19], v[230:231]
	v_pk_mul_f32 v[20:21], v[20:21], v[232:233]
	v_pk_mul_f32 v[22:23], v[22:23], v[234:235]
	v_pk_mul_f32 v[24:25], v[24:25], v[236:237]
	v_pk_mul_f32 v[26:27], v[26:27], v[238:239]
	v_pk_mul_f32 v[28:29], v[28:29], v[240:241]
	v_pk_mul_f32 v[30:31], v[30:31], v[242:243]

; #define SBAR() __builtin_amdgcn_sched_barrier(0)
; #define RESC(a) do { if (__any((a) < 1.f)) { if (hi == 0) al_l[r32] = (a); asm volatile("s_waitcnt lgkmcnt(0)" ::: "memory"); \
;     _Pragma("unroll") for (int d = 0; d < 4; ++d) _Pragma("unroll") for (int r = 0; r < 16; ++r) o[d][r] *= al_l[crow(r, hi)]; } } while (0)
; template <int D0> __device__ __forceinline__ void pv_one(f32x16& od, int vb, bf16x8 pa0, bf16x8 pa1, bf16x8 pa2, bf16x8 pa3) {
;   const s16x4 l0 = tr_read<v_rd_off(D0, 0, 0)>(vb), h0 = tr_read<v_rd_off(D0, 0, 1)>(vb), l1 = tr_read<v_rd_off(D0, 1, 0)>(vb), h1 = tr_read<v_rd_off(D0, 1, 1)>(vb);
;   const s16x4 l2 = tr_read<v_rd_off(D0, 2, 0)>(vb), h2 = tr_read<v_rd_off(D0, 2, 1)>(vb), l3 = tr_read<v_rd_off(D0, 3, 0)>(vb), h3 = tr_read<v_rd_off(D0, 3, 1)>(vb);
;   asm volatile("s_waitcnt lgkmcnt(0)" ::: "memory"); SBAR();
;     ...
;   od = __builtin_amdgcn_mfma_f32_32x32x16_bf16(pa0, PK(l0, h0), od, 0, 0, 0);
;   od = __builtin_amdgcn_mfma_f32_32x32x16_bf16(pa1, PK(l1, h1), od, 0, 0, 0);
;   od = __builtin_amdgcn_mfma_f32_32x32x16_bf16(pa2, PK(l2, h2), od, 0, 0, 0);
;   od = __builtin_amdgcn_mfma_f32_32x32x16_bf16(pa3, PK(l3, h3), od, 0, 0, 0);
;     ...
; }
; __device__ __forceinline__ void pv_d0(f32x16* o, int vb, bf16x8 pa0, bf16x8 pa1, bf16x8 pa2, bf16x8 pa3) {
;   pv_one<0>(o[0], vb, pa0, pa1, pa2, pa3); pv_one<1>(o[1], vb, pa0, pa1, pa2, pa3); pv_one<2>(o[2], vb, pa0, pa1, pa2, pa3); pv_one<3>(o[3], vb, pa0, pa1, pa2, pa3);
; template <int MODE, int SDEPTH>
; __device__ __forceinline__ void attn_unit(const UnitP& u, char* lds) {
;     ...
;   SBAR(); qkt(pB0, pB1, (bf16_t*)((char*)K_lds + SHM_K), qr, r32, hi);
;   finishSM(pA0, pA1, alA, l_reg, pa0, pa1, pa2, pa3); SBAR();
;   pv_d0(o, vb0, pa0, pa1, pa2, pa3); mask_tile<MODE>(pB0, pB1, u, NT - 1, wid, r32, hi, biasL); partialSM(pB0, pB1, m_reg, mnB, alB);
;   __syncthreads(); RESC(alB);
;   finishSM(pB0, pB1, alB, l_reg, pa0, pa1, pa2, pa3); SBAR();
;   pv_d0(o, vb0 + (int)SHM_V, pa0, pa1, pa2, pa3);
.Lda_skipk_3:
	s_barrier
	s_cmp_lt_u32 s31, 132
	s_cbranch_scc1 .Lda_loop
	s_setprio 1
	ds_read_b64_tr_b16 v[150:151], v196 offset:49152
	ds_read_b64_tr_b16 v[152:153], v196 offset:51200
	ds_read_b64_tr_b16 v[154:155], v196 offset:53248
	ds_read_b64_tr_b16 v[156:157], v196 offset:55296
	ds_read_b64_tr_b16 v[158:159], v196 offset:57344
	ds_read_b64_tr_b16 v[160:161], v196 offset:59392
	ds_read_b64_tr_b16 v[162:163], v196 offset:61440
	ds_read_b64_tr_b16 v[164:165], v196 offset:63488
	ds_read_b64_tr_b16 v[228:229], v196 offset:49664
	ds_read_b64_tr_b16 v[230:231], v196 offset:51712
	ds_read_b64_tr_b16 v[232:233], v196 offset:53760
	ds_read_b64_tr_b16 v[234:235], v196 offset:55808
	ds_read_b64_tr_b16 v[236:237], v196 offset:57856
	ds_read_b64_tr_b16 v[238:239], v196 offset:59904
	s_waitcnt lgkmcnt(12)
	v_mfma_f32_32x32x16_bf16 v[0:15], v[166:169], v[150:153], v[0:15]
	ds_read_b64_tr_b16 v[240:241], v196 offset:61952
	ds_read_b64_tr_b16 v[242:243], v196 offset:64000
	s_waitcnt lgkmcnt(12)
	v_mfma_f32_32x32x16_bf16 v[0:15], v[170:173], v[154:157], v[0:15]
	ds_read_b64_tr_b16 v[150:151], v196 offset:50176
	ds_read_b64_tr_b16 v[152:153], v196 offset:52224
	s_waitcnt lgkmcnt(12)
	v_mfma_f32_32x32x16_bf16 v[0:15], v[176:179], v[158:161], v[0:15]
	ds_read_b64_tr_b16 v[154:155], v196 offset:54272
	ds_read_b64_tr_b16 v[156:157], v196 offset:56320
	s_waitcnt lgkmcnt(12)
	v_mfma_f32_32x32x16_bf16 v[0:15], v[180:183], v[162:165], v[0:15]
	ds_read_b64_tr_b16 v[158:159], v196 offset:58368
	ds_read_b64_tr_b16 v[160:161], v196 offset:60416
	s_waitcnt lgkmcnt(12)
	v_mfma_f32_32x32x16_bf16 v[48:63], v[166:169], v[228:231], v[48:63]
	ds_read_b64_tr_b16 v[162:163], v196 offset:62464
	ds_read_b64_tr_b16 v[164:165], v196 offset:64512
	s_waitcnt lgkmcnt(12)
	v_mfma_f32_32x32x16_bf16 v[48:63], v[170:173], v[232:235], v[48:63]
	ds_read_b64_tr_b16 v[228:229], v196 offset:50688
	ds_read_b64_tr_b16 v[230:231], v196 offset:52736
	s_waitcnt lgkmcnt(12)
	v_mfma_f32_32x32x16_bf16 v[48:63], v[176:179], v[236:239], v[48:63]
	ds_read_b64_tr_b16 v[232:233], v196 offset:54784
	ds_read_b64_tr_b16 v[234:235], v196 offset:56832
	s_waitcnt lgkmcnt(12)
	v_mfma_f32_32x32x16_bf16 v[48:63], v[180:183], v[240:243], v[48:63]
	ds_read_b64_tr_b16 v[236:237], v196 offset:58880
	ds_read_b64_tr_b16 v[238:239], v196 offset:60928
	s_waitcnt lgkmcnt(12)
	v_mfma_f32_32x32x16_bf16 v[32:47], v[166:169], v[150:153], v[32:47]
	ds_read_b64_tr_b16 v[240:241], v196 offset:62976
	ds_read_b64_tr_b16 v[242:243], v196 offset:65024
	s_waitcnt lgkmcnt(12)
	v_mfma_f32_32x32x16_bf16 v[32:47], v[170:173], v[154:157], v[32:47]
	s_waitcnt lgkmcnt(10)
	v_mfma_f32_32x32x16_bf16 v[32:47], v[176:179], v[158:161], v[32:47]
	s_waitcnt lgkmcnt(8)
	v_mfma_f32_32x32x16_bf16 v[32:47], v[180:183], v[162:165], v[32:47]
	s_waitcnt lgkmcnt(6)
	v_mfma_f32_32x32x16_bf16 v[16:31], v[166:169], v[228:231], v[16:31]
	s_waitcnt lgkmcnt(4)
	v_mfma_f32_32x32x16_bf16 v[16:31], v[170:173], v[232:235], v[16:31]
	s_waitcnt lgkmcnt(2)
	v_mfma_f32_32x32x16_bf16 v[16:31], v[176:179], v[236:239], v[16:31]
	s_waitcnt lgkmcnt(0)
	v_mfma_f32_32x32x16_bf16 v[16:31], v[180:183], v[240:243], v[16:31]
	s_nop 12
	s_setprio 0
	s_cmp_lt_u32 s36, 4
	s_cbranch_scc0 .Lda_trail
	s_barrier
